# attnA group barrier: lane-0 arrival increment issued before the last four PV MFMAs of a step (they only touch registers)
# speedup vs baseline: 1.0247x; 1.0247x over previous
.LBB0_1369:
	s_or_b32 s82, s34, 1
	s_lshl_b64 s[4:5], s[82:83], 7
	s_add_u32 s4, s8, s4
	s_addc_u32 s5, s9, s5
	s_add_u32 m0, s38, 0x8000
	s_nop 0
	global_load_lds_dwordx4 v198, s[4:5]
	s_add_u32 m0, s38, 0x9000
	s_nop 0
	global_load_lds_dwordx4 v199, s[4:5]
	s_add_u32 m0, s38, 0xa000
	s_nop 0
	global_load_lds_dwordx4 v200, s[4:5]
	s_add_u32 m0, s38, 0xb000
	s_nop 0
	global_load_lds_dwordx4 v201, s[4:5]
	v_cmp_lt_i32_e64 s[4:5], s34, v226
	s_and_saveexec_b64 s[22:23], s[4:5]
	s_cbranch_execz .LBB0_1371
	ds_read_b128 v[2:5], v222 offset:24576
	ds_read_b128 v[6:9], v222 offset:28672
	ds_read_b128 v[10:13], v223 offset:24576
	ds_read_b128 v[244:247], v223 offset:28672
	s_waitcnt lgkmcnt(3)
	v_mfma_f32_32x32x16_bf16 v[128:143], v[2:5], v[160:163], v[16:31]
	v_exp_f32_e32 v32, v32
	v_exp_f32_e32 v33, v33
	ds_read_b128 v[2:5], v224 offset:24576
	s_waitcnt lgkmcnt(3)
	v_mfma_f32_32x32x16_bf16 v[144:159], v[6:9], v[160:163], v[16:31]
	v_exp_f32_e32 v34, v34
	v_exp_f32_e32 v35, v35
	ds_read_b128 v[6:9], v224 offset:28672
	s_waitcnt lgkmcnt(3)
	v_mfma_f32_32x32x16_bf16 v[128:143], v[10:13], v[164:167], v[128:143]
	v_exp_f32_e32 v36, v36
	v_exp_f32_e32 v37, v37
	v_add_f32_e32 v0, 0, v32
	ds_read_b128 v[10:13], v225 offset:24576
	s_waitcnt lgkmcnt(3)
	v_mfma_f32_32x32x16_bf16 v[144:159], v[244:247], v[164:167], v[144:159]
	v_exp_f32_e32 v38, v38
	v_exp_f32_e32 v39, v39
	v_add_f32_e32 v0, v33, v0
	ds_read_b128 v[244:247], v225 offset:28672
	s_waitcnt lgkmcnt(3)
	v_mfma_f32_32x32x16_bf16 v[128:143], v[2:5], v[168:171], v[128:143]
	v_cvt_pk_bf16_f32 v208, v32, v33
	v_add_f32_e32 v0, v34, v0
	v_add_f32_e32 v0, v35, v0
	s_waitcnt lgkmcnt(2)
	v_mfma_f32_32x32x16_bf16 v[144:159], v[6:9], v[168:171], v[144:159]
	v_cvt_pk_bf16_f32 v209, v34, v35
	v_add_f32_e32 v0, v36, v0
	v_add_f32_e32 v0, v37, v0
	s_waitcnt lgkmcnt(1)
	v_mfma_f32_32x32x16_bf16 v[128:143], v[10:13], v[172:175], v[128:143]
	v_cvt_pk_bf16_f32 v210, v36, v37
	v_add_f32_e32 v0, v38, v0
	s_waitcnt lgkmcnt(0)
	v_mfma_f32_32x32x16_bf16 v[144:159], v[244:247], v[172:175], v[144:159]
	v_cvt_pk_bf16_f32 v211, v38, v39
	v_add_f32_e32 v0, v39, v0
	s_or_b64 exec, exec, s[22:23]
	v_cmp_le_i32_e32 vcc, s34, v226
	s_and_saveexec_b64 s[22:23], vcc
	ds_read_b64 v[6:7], v228 offset:8192
	ds_read_b64 v[8:9], v229 offset:8192
	ds_read_b64 v[10:11], v230 offset:20480
	ds_read_b64 v[12:13], v231 offset:20480
	ds_read_b64 v[244:245], v230 offset:12288
	ds_read_b64 v[246:247], v231 offset:12288
	ds_read_b64 v[32:33], v230 offset:16384
	ds_read_b64 v[34:35], v231 offset:16384
	ds_read_b64 v[36:37], v232 offset:8192
	ds_read_b64 v[38:39], v233 offset:8192
	s_waitcnt lgkmcnt(8)
	v_mfma_f32_32x32x16_bf16 v[112:127], v[6:9], v[208:211], v[112:127]
	ds_read_b64 v[6:7], v234 offset:20480
	ds_read_b64 v[8:9], v235 offset:20480
	v_exp_f32_e32 v40, v40
	v_exp_f32_e32 v41, v41
	s_waitcnt lgkmcnt(8)
	v_mfma_f32_32x32x16_bf16 v[64:79], v[10:13], v[208:211], v[64:79]
	ds_read_b64 v[10:11], v234 offset:12288
	ds_read_b64 v[12:13], v235 offset:12288
	v_exp_f32_e32 v42, v42
	v_exp_f32_e32 v43, v43
	v_add_f32_e32 v0, v40, v0
	v_add_f32_e32 v0, v41, v0
	s_waitcnt lgkmcnt(8)
	v_mfma_f32_32x32x16_bf16 v[96:111], v[244:247], v[208:211], v[96:111]
	ds_read_b64 v[244:245], v234 offset:16384
	ds_read_b64 v[246:247], v235 offset:16384
	v_exp_f32_e32 v44, v44
	v_exp_f32_e32 v45, v45
	v_add_f32_e32 v0, v42, v0
	v_add_f32_e32 v0, v43, v0
	s_waitcnt lgkmcnt(8)
	v_mfma_f32_32x32x16_bf16 v[80:95], v[32:35], v[208:211], v[80:95]
	ds_read_b64 v[32:33], v236 offset:8192
	ds_read_b64 v[34:35], v237 offset:8192
	v_exp_f32_e32 v46, v46
	v_exp_f32_e32 v47, v47
	v_add_f32_e32 v0, v44, v0
	v_add_f32_e32 v0, v45, v0
	v_add_f32_e32 v0, v46, v0
	v_add_f32_e32 v0, v47, v0
	v_cvt_pk_bf16_f32 v2, v40, v41
	v_cvt_pk_bf16_f32 v3, v42, v43
	v_cvt_pk_bf16_f32 v4, v44, v45
	v_cvt_pk_bf16_f32 v5, v46, v47
	s_nop 1
	ds_read_b64 v[40:41], v238 offset:20480
	ds_read_b64 v[42:43], v239 offset:20480
	s_waitcnt lgkmcnt(10)
	v_mfma_f32_32x32x16_bf16 v[112:127], v[36:39], v[2:5], v[112:127]
	ds_read_b64 v[44:45], v238 offset:12288
	ds_read_b64 v[46:47], v239 offset:12288
	v_exp_f32_e32 v48, v48
	v_exp_f32_e32 v49, v49
	s_waitcnt lgkmcnt(10)
	v_mfma_f32_32x32x16_bf16 v[64:79], v[6:9], v[2:5], v[64:79]
	ds_read_b64 v[36:37], v238 offset:16384
	ds_read_b64 v[38:39], v239 offset:16384
	v_exp_f32_e32 v50, v50
	v_exp_f32_e32 v51, v51
	v_add_f32_e32 v0, v48, v0
	v_add_f32_e32 v0, v49, v0
	s_waitcnt lgkmcnt(10)
	v_mfma_f32_32x32x16_bf16 v[96:111], v[10:13], v[2:5], v[96:111]
	ds_read_b64 v[6:7], v240 offset:8192
	ds_read_b64 v[8:9], v241 offset:8192
	v_exp_f32_e32 v52, v52
	v_exp_f32_e32 v53, v53
	v_add_f32_e32 v0, v50, v0
	v_add_f32_e32 v0, v51, v0
	s_waitcnt lgkmcnt(10)
	v_mfma_f32_32x32x16_bf16 v[80:95], v[244:247], v[2:5], v[80:95]
	ds_read_b64 v[10:11], v242 offset:12288
	ds_read_b64 v[12:13], v243 offset:12288
	v_exp_f32_e32 v54, v54
	v_exp_f32_e32 v55, v55
	v_add_f32_e32 v0, v52, v0
	v_add_f32_e32 v0, v53, v0
	v_add_f32_e32 v0, v54, v0
	v_add_f32_e32 v0, v55, v0
	v_cvt_pk_bf16_f32 v2, v48, v49
	v_cvt_pk_bf16_f32 v3, v50, v51
	v_cvt_pk_bf16_f32 v4, v52, v53
	v_cvt_pk_bf16_f32 v5, v54, v55
	s_nop 1
	ds_read_b64 v[244:245], v242 offset:16384
	ds_read_b64 v[246:247], v243 offset:16384
	s_waitcnt lgkmcnt(12)
	v_mfma_f32_32x32x16_bf16 v[112:127], v[32:35], v[2:5], v[112:127]
	ds_read_b64 v[48:49], v242 offset:20480
	ds_read_b64 v[50:51], v243 offset:20480
	v_exp_f32_e32 v56, v56
	v_exp_f32_e32 v57, v57
	s_waitcnt lgkmcnt(12)
	v_mfma_f32_32x32x16_bf16 v[64:79], v[40:43], v[2:5], v[64:79]
	v_exp_f32_e32 v58, v58
	v_exp_f32_e32 v59, v59
	v_add_f32_e32 v0, v56, v0
	v_add_f32_e32 v0, v57, v0
	s_waitcnt lgkmcnt(10)
	v_mfma_f32_32x32x16_bf16 v[96:111], v[44:47], v[2:5], v[96:111]
	v_exp_f32_e32 v60, v60
	v_exp_f32_e32 v61, v61
	v_add_f32_e32 v0, v58, v0
	v_add_f32_e32 v0, v59, v0
	s_waitcnt lgkmcnt(8)
	v_mfma_f32_32x32x16_bf16 v[80:95], v[36:39], v[2:5], v[80:95]
	v_exp_f32_e32 v62, v62
	v_exp_f32_e32 v63, v63
	v_add_f32_e32 v0, v60, v0
	v_add_f32_e32 v0, v61, v0
	v_add_f32_e32 v0, v62, v0
	v_add_f32_e32 v0, v63, v0
	v_cvt_pk_bf16_f32 v2, v56, v57
	v_cvt_pk_bf16_f32 v3, v58, v59
	v_cvt_pk_bf16_f32 v4, v60, v61
	v_cvt_pk_bf16_f32 v5, v62, v63
	s_nop 1
	s_waitcnt vmcnt(0) lgkmcnt(0)
	s_mov_b64 s[24:25], exec
	s_mov_b64 exec, 1
	v_mov_b32_e32 v248, s33
	v_mov_b32_e32 v249, 1
	ds_add_u32 v248, v249 offset:8
	s_mov_b64 exec, s[24:25]
	s_waitcnt lgkmcnt(6)
	v_mfma_f32_32x32x16_bf16 v[112:127], v[6:9], v[2:5], v[112:127]
	s_waitcnt lgkmcnt(4)
	v_mfma_f32_32x32x16_bf16 v[96:111], v[10:13], v[2:5], v[96:111]
	s_waitcnt lgkmcnt(2)
	v_mfma_f32_32x32x16_bf16 v[80:95], v[244:247], v[2:5], v[80:95]
	s_waitcnt lgkmcnt(0)
	v_mfma_f32_32x32x16_bf16 v[64:79], v[48:51], v[2:5], v[64:79]
	v_add_f32_e32 v227, v227, v0
	s_branch .LBB0_1376

.LBB0_1381:
	ds_read_b128 v[2:5], v222
	ds_read_b128 v[6:9], v222 offset:4096
	ds_read_b128 v[10:13], v223
	ds_read_b128 v[244:247], v223 offset:4096
	s_waitcnt lgkmcnt(3)
	v_mfma_f32_32x32x16_bf16 v[32:47], v[2:5], v[160:163], v[16:31]
	v_exp_f32_e32 v128, v128
	v_exp_f32_e32 v129, v129
	ds_read_b128 v[2:5], v224
	s_waitcnt lgkmcnt(3)
	v_mfma_f32_32x32x16_bf16 v[48:63], v[6:9], v[160:163], v[16:31]
	v_exp_f32_e32 v130, v130
	v_exp_f32_e32 v131, v131
	ds_read_b128 v[6:9], v224 offset:4096
	s_waitcnt lgkmcnt(3)
	v_mfma_f32_32x32x16_bf16 v[32:47], v[10:13], v[164:167], v[32:47]
	v_exp_f32_e32 v132, v132
	v_exp_f32_e32 v133, v133
	v_add_f32_e32 v0, 0, v128
	ds_read_b128 v[10:13], v225
	s_waitcnt lgkmcnt(3)
	v_mfma_f32_32x32x16_bf16 v[48:63], v[244:247], v[164:167], v[48:63]
	v_exp_f32_e32 v134, v134
	v_exp_f32_e32 v135, v135
	v_add_f32_e32 v0, v129, v0
	ds_read_b128 v[244:247], v225 offset:4096
	s_waitcnt lgkmcnt(3)
	v_mfma_f32_32x32x16_bf16 v[32:47], v[2:5], v[168:171], v[32:47]
	v_cvt_pk_bf16_f32 v208, v128, v129
	v_add_f32_e32 v0, v130, v0
	v_add_f32_e32 v0, v131, v0
	s_waitcnt lgkmcnt(2)
	v_mfma_f32_32x32x16_bf16 v[48:63], v[6:9], v[168:171], v[48:63]
	v_cvt_pk_bf16_f32 v209, v130, v131
	v_add_f32_e32 v0, v132, v0
	v_add_f32_e32 v0, v133, v0
	s_waitcnt lgkmcnt(1)
	v_mfma_f32_32x32x16_bf16 v[32:47], v[10:13], v[172:175], v[32:47]
	v_cvt_pk_bf16_f32 v210, v132, v133
	v_add_f32_e32 v0, v134, v0
	s_waitcnt lgkmcnt(0)
	v_mfma_f32_32x32x16_bf16 v[48:63], v[244:247], v[172:175], v[48:63]
	v_cvt_pk_bf16_f32 v211, v134, v135
	v_add_f32_e32 v0, v135, v0
	s_or_b64 exec, exec, s[20:21]
	s_and_saveexec_b64 s[20:21], s[4:5]
	ds_read_b64 v[6:7], v228 offset:32768
	ds_read_b64 v[8:9], v229 offset:32768
	ds_read_b64 v[10:11], v230 offset:45056
	ds_read_b64 v[12:13], v231 offset:45056
	ds_read_b64 v[244:245], v230 offset:36864
	ds_read_b64 v[246:247], v231 offset:36864
	ds_read_b64 v[128:129], v230 offset:40960
	ds_read_b64 v[130:131], v231 offset:40960
	ds_read_b64 v[132:133], v232 offset:32768
	ds_read_b64 v[134:135], v233 offset:32768
	s_waitcnt lgkmcnt(8)
	v_mfma_f32_32x32x16_bf16 v[112:127], v[6:9], v[208:211], v[112:127]
	ds_read_b64 v[6:7], v234 offset:45056
	ds_read_b64 v[8:9], v235 offset:45056
	v_exp_f32_e32 v136, v136
	v_exp_f32_e32 v137, v137
	s_waitcnt lgkmcnt(8)
	v_mfma_f32_32x32x16_bf16 v[64:79], v[10:13], v[208:211], v[64:79]
	ds_read_b64 v[10:11], v234 offset:36864
	ds_read_b64 v[12:13], v235 offset:36864
	v_exp_f32_e32 v138, v138
	v_exp_f32_e32 v139, v139
	v_add_f32_e32 v0, v136, v0
	v_add_f32_e32 v0, v137, v0
	s_waitcnt lgkmcnt(8)
	v_mfma_f32_32x32x16_bf16 v[96:111], v[244:247], v[208:211], v[96:111]
	ds_read_b64 v[244:245], v234 offset:40960
	ds_read_b64 v[246:247], v235 offset:40960
	v_exp_f32_e32 v140, v140
	v_exp_f32_e32 v141, v141
	v_add_f32_e32 v0, v138, v0
	v_add_f32_e32 v0, v139, v0
	s_waitcnt lgkmcnt(8)
	v_mfma_f32_32x32x16_bf16 v[80:95], v[128:131], v[208:211], v[80:95]
	ds_read_b64 v[128:129], v236 offset:32768
	ds_read_b64 v[130:131], v237 offset:32768
	v_exp_f32_e32 v142, v142
	v_exp_f32_e32 v143, v143
	v_add_f32_e32 v0, v140, v0
	v_add_f32_e32 v0, v141, v0
	v_add_f32_e32 v0, v142, v0
	v_add_f32_e32 v0, v143, v0
	v_cvt_pk_bf16_f32 v2, v136, v137
	v_cvt_pk_bf16_f32 v3, v138, v139
	v_cvt_pk_bf16_f32 v4, v140, v141
	v_cvt_pk_bf16_f32 v5, v142, v143
	s_nop 1
	ds_read_b64 v[136:137], v238 offset:45056
	ds_read_b64 v[138:139], v239 offset:45056
	s_waitcnt lgkmcnt(10)
	v_mfma_f32_32x32x16_bf16 v[112:127], v[132:135], v[2:5], v[112:127]
	ds_read_b64 v[140:141], v238 offset:36864
	ds_read_b64 v[142:143], v239 offset:36864
	v_exp_f32_e32 v144, v144
	v_exp_f32_e32 v145, v145
	s_waitcnt lgkmcnt(10)
	v_mfma_f32_32x32x16_bf16 v[64:79], v[6:9], v[2:5], v[64:79]
	ds_read_b64 v[132:133], v238 offset:40960
	ds_read_b64 v[134:135], v239 offset:40960
	v_exp_f32_e32 v146, v146
	v_exp_f32_e32 v147, v147
	v_add_f32_e32 v0, v144, v0
	v_add_f32_e32 v0, v145, v0
	s_waitcnt lgkmcnt(10)
	v_mfma_f32_32x32x16_bf16 v[96:111], v[10:13], v[2:5], v[96:111]
	ds_read_b64 v[6:7], v240 offset:32768
	ds_read_b64 v[8:9], v241 offset:32768
	v_exp_f32_e32 v148, v148
	v_exp_f32_e32 v149, v149
	v_add_f32_e32 v0, v146, v0
	v_add_f32_e32 v0, v147, v0
	s_waitcnt lgkmcnt(10)
	v_mfma_f32_32x32x16_bf16 v[80:95], v[244:247], v[2:5], v[80:95]
	ds_read_b64 v[10:11], v242 offset:36864
	ds_read_b64 v[12:13], v243 offset:36864
	v_exp_f32_e32 v150, v150
	v_exp_f32_e32 v151, v151
	v_add_f32_e32 v0, v148, v0
	v_add_f32_e32 v0, v149, v0
	v_add_f32_e32 v0, v150, v0
	v_add_f32_e32 v0, v151, v0
	v_cvt_pk_bf16_f32 v2, v144, v145
	v_cvt_pk_bf16_f32 v3, v146, v147
	v_cvt_pk_bf16_f32 v4, v148, v149
	v_cvt_pk_bf16_f32 v5, v150, v151
	s_nop 1
	ds_read_b64 v[244:245], v242 offset:40960
	ds_read_b64 v[246:247], v243 offset:40960
	s_waitcnt lgkmcnt(12)
	v_mfma_f32_32x32x16_bf16 v[112:127], v[128:131], v[2:5], v[112:127]
	ds_read_b64 v[144:145], v242 offset:45056
	ds_read_b64 v[146:147], v243 offset:45056
	v_exp_f32_e32 v152, v152
	v_exp_f32_e32 v153, v153
	s_waitcnt lgkmcnt(12)
	v_mfma_f32_32x32x16_bf16 v[64:79], v[136:139], v[2:5], v[64:79]
	v_exp_f32_e32 v154, v154
	v_exp_f32_e32 v155, v155
	v_add_f32_e32 v0, v152, v0
	v_add_f32_e32 v0, v153, v0
	s_waitcnt lgkmcnt(10)
	v_mfma_f32_32x32x16_bf16 v[96:111], v[140:143], v[2:5], v[96:111]
	v_exp_f32_e32 v156, v156
	v_exp_f32_e32 v157, v157
	v_add_f32_e32 v0, v154, v0
	v_add_f32_e32 v0, v155, v0
	s_waitcnt lgkmcnt(8)
	v_mfma_f32_32x32x16_bf16 v[80:95], v[132:135], v[2:5], v[80:95]
	v_exp_f32_e32 v158, v158
	v_exp_f32_e32 v159, v159
	v_add_f32_e32 v0, v156, v0
	v_add_f32_e32 v0, v157, v0
	v_add_f32_e32 v0, v158, v0
	v_add_f32_e32 v0, v159, v0
	v_cvt_pk_bf16_f32 v2, v152, v153
	v_cvt_pk_bf16_f32 v3, v154, v155
	v_cvt_pk_bf16_f32 v4, v156, v157
	v_cvt_pk_bf16_f32 v5, v158, v159
	s_nop 1
	s_waitcnt vmcnt(0) lgkmcnt(0)
	s_mov_b64 s[24:25], exec
	s_mov_b64 exec, 1
	v_mov_b32_e32 v248, s33
	v_mov_b32_e32 v249, 1
	ds_add_u32 v248, v249 offset:8
	s_mov_b64 exec, s[24:25]
	s_waitcnt lgkmcnt(6)
	v_mfma_f32_32x32x16_bf16 v[112:127], v[6:9], v[2:5], v[112:127]
	s_waitcnt lgkmcnt(4)
	v_mfma_f32_32x32x16_bf16 v[96:111], v[10:13], v[2:5], v[96:111]
	s_waitcnt lgkmcnt(2)
	v_mfma_f32_32x32x16_bf16 v[80:95], v[244:247], v[2:5], v[80:95]
	s_waitcnt lgkmcnt(0)
	v_mfma_f32_32x32x16_bf16 v[64:79], v[144:147], v[2:5], v[64:79]
	v_add_f32_e32 v227, v0, v227
	s_or_b64 exec, exec, s[20:21]
	s_branch .LBB0_1389

.LBB0_1411:
	s_or_b32 s82, s31, 1
	s_lshl_b64 s[4:5], s[82:83], 7
	s_add_u32 s4, s8, s4
	s_addc_u32 s5, s9, s5
	s_add_u32 m0, s38, 0x8000
	s_nop 0
	global_load_lds_dwordx4 v196, s[4:5]
	s_add_u32 m0, s38, 0x9000
	s_nop 0
	global_load_lds_dwordx4 v197, s[4:5]
	s_add_u32 m0, s38, 0xa000
	s_nop 0
	global_load_lds_dwordx4 v198, s[4:5]
	s_add_u32 m0, s38, 0xb000
	s_nop 0
	global_load_lds_dwordx4 v199, s[4:5]
	v_cmp_lt_i32_e64 s[4:5], s31, v225
	s_and_saveexec_b64 s[22:23], s[4:5]
	s_cbranch_execz .LBB0_1413
	ds_read_b128 v[2:5], v220 offset:24576
	ds_read_b128 v[6:9], v220 offset:28672
	ds_read_b128 v[10:13], v221 offset:24576
	ds_read_b128 v[244:247], v221 offset:28672
	s_waitcnt lgkmcnt(3)
	v_mfma_f32_32x32x16_bf16 v[128:143], v[2:5], v[160:163], v[16:31]
	v_exp_f32_e32 v80, v80
	v_exp_f32_e32 v81, v81
	ds_read_b128 v[2:5], v222 offset:24576
	s_waitcnt lgkmcnt(3)
	v_mfma_f32_32x32x16_bf16 v[144:159], v[6:9], v[160:163], v[16:31]
	v_exp_f32_e32 v82, v82
	v_exp_f32_e32 v83, v83
	ds_read_b128 v[6:9], v222 offset:28672
	s_waitcnt lgkmcnt(3)
	v_mfma_f32_32x32x16_bf16 v[128:143], v[10:13], v[164:167], v[128:143]
	v_exp_f32_e32 v84, v84
	v_exp_f32_e32 v85, v85
	v_add_f32_e32 v0, 0, v80
	ds_read_b128 v[10:13], v223 offset:24576
	s_waitcnt lgkmcnt(3)
	v_mfma_f32_32x32x16_bf16 v[144:159], v[244:247], v[164:167], v[144:159]
	v_exp_f32_e32 v86, v86
	v_exp_f32_e32 v87, v87
	v_add_f32_e32 v0, v81, v0
	ds_read_b128 v[244:247], v223 offset:28672
	s_waitcnt lgkmcnt(3)
	v_mfma_f32_32x32x16_bf16 v[128:143], v[2:5], v[168:171], v[128:143]
	v_cvt_pk_bf16_f32 v208, v80, v81
	v_add_f32_e32 v0, v82, v0
	v_add_f32_e32 v0, v83, v0
	s_waitcnt lgkmcnt(2)
	v_mfma_f32_32x32x16_bf16 v[144:159], v[6:9], v[168:171], v[144:159]
	v_cvt_pk_bf16_f32 v209, v82, v83
	v_add_f32_e32 v0, v84, v0
	v_add_f32_e32 v0, v85, v0
	s_waitcnt lgkmcnt(1)
	v_mfma_f32_32x32x16_bf16 v[128:143], v[10:13], v[172:175], v[128:143]
	v_cvt_pk_bf16_f32 v210, v84, v85
	v_add_f32_e32 v0, v86, v0
	s_waitcnt lgkmcnt(0)
	v_mfma_f32_32x32x16_bf16 v[144:159], v[244:247], v[172:175], v[144:159]
	v_cvt_pk_bf16_f32 v211, v86, v87
	v_add_f32_e32 v0, v87, v0
	s_or_b64 exec, exec, s[22:23]
	v_cmp_le_i32_e32 vcc, s31, v225
	s_and_saveexec_b64 s[22:23], vcc
	ds_read_b64 v[6:7], v226 offset:8192
	ds_read_b64 v[8:9], v227 offset:8192
	ds_read_b64 v[10:11], v228 offset:20480
	ds_read_b64 v[12:13], v229 offset:20480
	ds_read_b64 v[242:243], v228 offset:12288
	ds_read_b64 v[244:245], v229 offset:12288
	ds_read_b64 v[80:81], v228 offset:16384
	ds_read_b64 v[82:83], v229 offset:16384
	ds_read_b64 v[84:85], v230 offset:8192
	ds_read_b64 v[86:87], v231 offset:8192
	s_waitcnt lgkmcnt(8)
	v_mfma_f32_32x32x16_bf16 v[64:79], v[6:9], v[208:211], v[64:79]
	ds_read_b64 v[6:7], v232 offset:20480
	ds_read_b64 v[8:9], v233 offset:20480
	v_exp_f32_e32 v88, v88
	v_exp_f32_e32 v89, v89
	s_waitcnt lgkmcnt(8)
	v_mfma_f32_32x32x16_bf16 v[112:127], v[10:13], v[208:211], v[112:127]
	ds_read_b64 v[10:11], v232 offset:12288
	ds_read_b64 v[12:13], v233 offset:12288
	v_exp_f32_e32 v90, v90
	v_exp_f32_e32 v91, v91
	v_add_f32_e32 v0, v88, v0
	v_add_f32_e32 v0, v89, v0
	s_waitcnt lgkmcnt(8)
	v_mfma_f32_32x32x16_bf16 v[48:63], v[242:245], v[208:211], v[48:63]
	ds_read_b64 v[242:243], v232 offset:16384
	ds_read_b64 v[244:245], v233 offset:16384
	v_exp_f32_e32 v92, v92
	v_exp_f32_e32 v93, v93
	v_add_f32_e32 v0, v90, v0
	v_add_f32_e32 v0, v91, v0
	s_waitcnt lgkmcnt(8)
	v_mfma_f32_32x32x16_bf16 v[32:47], v[80:83], v[208:211], v[32:47]
	ds_read_b64 v[80:81], v234 offset:8192
	ds_read_b64 v[82:83], v235 offset:8192
	v_exp_f32_e32 v94, v94
	v_exp_f32_e32 v95, v95
	v_add_f32_e32 v0, v92, v0
	v_add_f32_e32 v0, v93, v0
	v_add_f32_e32 v0, v94, v0
	v_add_f32_e32 v0, v95, v0
	v_cvt_pk_bf16_f32 v2, v88, v89
	v_cvt_pk_bf16_f32 v3, v90, v91
	v_cvt_pk_bf16_f32 v4, v92, v93
	v_cvt_pk_bf16_f32 v5, v94, v95
	s_nop 1
	ds_read_b64 v[88:89], v236 offset:20480
	ds_read_b64 v[90:91], v237 offset:20480
	s_waitcnt lgkmcnt(10)
	v_mfma_f32_32x32x16_bf16 v[64:79], v[84:87], v[2:5], v[64:79]
	ds_read_b64 v[92:93], v236 offset:12288
	ds_read_b64 v[94:95], v237 offset:12288
	v_exp_f32_e32 v96, v96
	v_exp_f32_e32 v97, v97
	s_waitcnt lgkmcnt(10)
	v_mfma_f32_32x32x16_bf16 v[112:127], v[6:9], v[2:5], v[112:127]
	ds_read_b64 v[84:85], v236 offset:16384
	ds_read_b64 v[86:87], v237 offset:16384
	v_exp_f32_e32 v98, v98
	v_exp_f32_e32 v99, v99
	v_add_f32_e32 v0, v96, v0
	v_add_f32_e32 v0, v97, v0
	s_waitcnt lgkmcnt(10)
	v_mfma_f32_32x32x16_bf16 v[48:63], v[10:13], v[2:5], v[48:63]
	ds_read_b64 v[6:7], v238 offset:8192
	ds_read_b64 v[8:9], v239 offset:8192
	v_exp_f32_e32 v100, v100
	v_exp_f32_e32 v101, v101
	v_add_f32_e32 v0, v98, v0
	v_add_f32_e32 v0, v99, v0
	s_waitcnt lgkmcnt(10)
	v_mfma_f32_32x32x16_bf16 v[32:47], v[242:245], v[2:5], v[32:47]
	ds_read_b64 v[10:11], v240 offset:12288
	ds_read_b64 v[12:13], v241 offset:12288
	v_exp_f32_e32 v102, v102
	v_exp_f32_e32 v103, v103
	v_add_f32_e32 v0, v100, v0
	v_add_f32_e32 v0, v101, v0
	v_add_f32_e32 v0, v102, v0
	v_add_f32_e32 v0, v103, v0
	v_cvt_pk_bf16_f32 v2, v96, v97
	v_cvt_pk_bf16_f32 v3, v98, v99
	v_cvt_pk_bf16_f32 v4, v100, v101
	v_cvt_pk_bf16_f32 v5, v102, v103
	s_nop 1
	ds_read_b64 v[242:243], v240 offset:16384
	ds_read_b64 v[244:245], v241 offset:16384
	s_waitcnt lgkmcnt(12)
	v_mfma_f32_32x32x16_bf16 v[64:79], v[80:83], v[2:5], v[64:79]
	ds_read_b64 v[96:97], v240 offset:20480
	ds_read_b64 v[98:99], v241 offset:20480
	v_exp_f32_e32 v104, v104
	v_exp_f32_e32 v105, v105
	s_waitcnt lgkmcnt(12)
	v_mfma_f32_32x32x16_bf16 v[112:127], v[88:91], v[2:5], v[112:127]
	v_exp_f32_e32 v106, v106
	v_exp_f32_e32 v107, v107
	v_add_f32_e32 v0, v104, v0
	v_add_f32_e32 v0, v105, v0
	s_waitcnt lgkmcnt(10)
	v_mfma_f32_32x32x16_bf16 v[48:63], v[92:95], v[2:5], v[48:63]
	v_exp_f32_e32 v108, v108
	v_exp_f32_e32 v109, v109
	v_add_f32_e32 v0, v106, v0
	v_add_f32_e32 v0, v107, v0
	s_waitcnt lgkmcnt(8)
	v_mfma_f32_32x32x16_bf16 v[32:47], v[84:87], v[2:5], v[32:47]
	v_exp_f32_e32 v110, v110
	v_exp_f32_e32 v111, v111
	v_add_f32_e32 v0, v108, v0
	v_add_f32_e32 v0, v109, v0
	v_add_f32_e32 v0, v110, v0
	v_add_f32_e32 v0, v111, v0
	v_cvt_pk_bf16_f32 v2, v104, v105
	v_cvt_pk_bf16_f32 v3, v106, v107
	v_cvt_pk_bf16_f32 v4, v108, v109
	v_cvt_pk_bf16_f32 v5, v110, v111
	s_nop 1
	s_waitcnt vmcnt(0) lgkmcnt(0)
	s_mov_b64 s[24:25], exec
	s_mov_b64 exec, 1
	v_mov_b32_e32 v248, s33
	v_mov_b32_e32 v249, 1
	ds_add_u32 v248, v249 offset:8
	s_mov_b64 exec, s[24:25]
	s_waitcnt lgkmcnt(6)
	v_mfma_f32_32x32x16_bf16 v[64:79], v[6:9], v[2:5], v[64:79]
	s_waitcnt lgkmcnt(4)
	v_mfma_f32_32x32x16_bf16 v[48:63], v[10:13], v[2:5], v[48:63]
	s_waitcnt lgkmcnt(2)
	v_mfma_f32_32x32x16_bf16 v[32:47], v[242:245], v[2:5], v[32:47]
	s_waitcnt lgkmcnt(0)
	v_mfma_f32_32x32x16_bf16 v[112:127], v[96:99], v[2:5], v[112:127]
	v_add_f32_e32 v224, v224, v0
	s_branch .LBB0_1418

.LBB0_1423:
	ds_read_b128 v[2:5], v220
	ds_read_b128 v[6:9], v220 offset:4096
	ds_read_b128 v[10:13], v221
	ds_read_b128 v[244:247], v221 offset:4096
	s_waitcnt lgkmcnt(3)
	v_mfma_f32_32x32x16_bf16 v[80:95], v[2:5], v[160:163], v[16:31]
	v_exp_f32_e32 v128, v128
	v_exp_f32_e32 v129, v129
	ds_read_b128 v[2:5], v222
	s_waitcnt lgkmcnt(3)
	v_mfma_f32_32x32x16_bf16 v[96:111], v[6:9], v[160:163], v[16:31]
	v_exp_f32_e32 v130, v130
	v_exp_f32_e32 v131, v131
	ds_read_b128 v[6:9], v222 offset:4096
	s_waitcnt lgkmcnt(3)
	v_mfma_f32_32x32x16_bf16 v[80:95], v[10:13], v[164:167], v[80:95]
	v_exp_f32_e32 v132, v132
	v_exp_f32_e32 v133, v133
	v_add_f32_e32 v0, 0, v128
	ds_read_b128 v[10:13], v223
	s_waitcnt lgkmcnt(3)
	v_mfma_f32_32x32x16_bf16 v[96:111], v[244:247], v[164:167], v[96:111]
	v_exp_f32_e32 v134, v134
	v_exp_f32_e32 v135, v135
	v_add_f32_e32 v0, v129, v0
	ds_read_b128 v[244:247], v223 offset:4096
	s_waitcnt lgkmcnt(3)
	v_mfma_f32_32x32x16_bf16 v[80:95], v[2:5], v[168:171], v[80:95]
	v_cvt_pk_bf16_f32 v208, v128, v129
	v_add_f32_e32 v0, v130, v0
	v_add_f32_e32 v0, v131, v0
	s_waitcnt lgkmcnt(2)
	v_mfma_f32_32x32x16_bf16 v[96:111], v[6:9], v[168:171], v[96:111]
	v_cvt_pk_bf16_f32 v209, v130, v131
	v_add_f32_e32 v0, v132, v0
	v_add_f32_e32 v0, v133, v0
	s_waitcnt lgkmcnt(1)
	v_mfma_f32_32x32x16_bf16 v[80:95], v[10:13], v[172:175], v[80:95]
	v_cvt_pk_bf16_f32 v210, v132, v133
	v_add_f32_e32 v0, v134, v0
	s_waitcnt lgkmcnt(0)
	v_mfma_f32_32x32x16_bf16 v[96:111], v[244:247], v[172:175], v[96:111]
	v_cvt_pk_bf16_f32 v211, v134, v135
	v_add_f32_e32 v0, v135, v0
	s_or_b64 exec, exec, s[20:21]
	s_and_saveexec_b64 s[20:21], s[4:5]
	ds_read_b64 v[6:7], v226 offset:32768
	ds_read_b64 v[8:9], v227 offset:32768
	ds_read_b64 v[10:11], v228 offset:45056
	ds_read_b64 v[12:13], v229 offset:45056
	ds_read_b64 v[242:243], v228 offset:36864
	ds_read_b64 v[244:245], v229 offset:36864
	ds_read_b64 v[128:129], v228 offset:40960
	ds_read_b64 v[130:131], v229 offset:40960
	ds_read_b64 v[132:133], v230 offset:32768
	ds_read_b64 v[134:135], v231 offset:32768
	s_waitcnt lgkmcnt(8)
	v_mfma_f32_32x32x16_bf16 v[64:79], v[6:9], v[208:211], v[64:79]
	ds_read_b64 v[6:7], v232 offset:45056
	ds_read_b64 v[8:9], v233 offset:45056
	v_exp_f32_e32 v136, v136
	v_exp_f32_e32 v137, v137
	s_waitcnt lgkmcnt(8)
	v_mfma_f32_32x32x16_bf16 v[112:127], v[10:13], v[208:211], v[112:127]
	ds_read_b64 v[10:11], v232 offset:36864
	ds_read_b64 v[12:13], v233 offset:36864
	v_exp_f32_e32 v138, v138
	v_exp_f32_e32 v139, v139
	v_add_f32_e32 v0, v136, v0
	v_add_f32_e32 v0, v137, v0
	s_waitcnt lgkmcnt(8)
	v_mfma_f32_32x32x16_bf16 v[48:63], v[242:245], v[208:211], v[48:63]
	ds_read_b64 v[242:243], v232 offset:40960
	ds_read_b64 v[244:245], v233 offset:40960
	v_exp_f32_e32 v140, v140
	v_exp_f32_e32 v141, v141
	v_add_f32_e32 v0, v138, v0
	v_add_f32_e32 v0, v139, v0
	s_waitcnt lgkmcnt(8)
	v_mfma_f32_32x32x16_bf16 v[32:47], v[128:131], v[208:211], v[32:47]
	ds_read_b64 v[128:129], v234 offset:32768
	ds_read_b64 v[130:131], v235 offset:32768
	v_exp_f32_e32 v142, v142
	v_exp_f32_e32 v143, v143
	v_add_f32_e32 v0, v140, v0
	v_add_f32_e32 v0, v141, v0
	v_add_f32_e32 v0, v142, v0
	v_add_f32_e32 v0, v143, v0
	v_cvt_pk_bf16_f32 v2, v136, v137
	v_cvt_pk_bf16_f32 v3, v138, v139
	v_cvt_pk_bf16_f32 v4, v140, v141
	v_cvt_pk_bf16_f32 v5, v142, v143
	s_nop 1
	ds_read_b64 v[136:137], v236 offset:45056
	ds_read_b64 v[138:139], v237 offset:45056
	s_waitcnt lgkmcnt(10)
	v_mfma_f32_32x32x16_bf16 v[64:79], v[132:135], v[2:5], v[64:79]
	ds_read_b64 v[140:141], v236 offset:36864
	ds_read_b64 v[142:143], v237 offset:36864
	v_exp_f32_e32 v144, v144
	v_exp_f32_e32 v145, v145
	s_waitcnt lgkmcnt(10)
	v_mfma_f32_32x32x16_bf16 v[112:127], v[6:9], v[2:5], v[112:127]
	ds_read_b64 v[132:133], v236 offset:40960
	ds_read_b64 v[134:135], v237 offset:40960
	v_exp_f32_e32 v146, v146
	v_exp_f32_e32 v147, v147
	v_add_f32_e32 v0, v144, v0
	v_add_f32_e32 v0, v145, v0
	s_waitcnt lgkmcnt(10)
	v_mfma_f32_32x32x16_bf16 v[48:63], v[10:13], v[2:5], v[48:63]
	ds_read_b64 v[6:7], v238 offset:32768
	ds_read_b64 v[8:9], v239 offset:32768
	v_exp_f32_e32 v148, v148
	v_exp_f32_e32 v149, v149
	v_add_f32_e32 v0, v146, v0
	v_add_f32_e32 v0, v147, v0
	s_waitcnt lgkmcnt(10)
	v_mfma_f32_32x32x16_bf16 v[32:47], v[242:245], v[2:5], v[32:47]
	ds_read_b64 v[10:11], v240 offset:36864
	ds_read_b64 v[12:13], v241 offset:36864
	v_exp_f32_e32 v150, v150
	v_exp_f32_e32 v151, v151
	v_add_f32_e32 v0, v148, v0
	v_add_f32_e32 v0, v149, v0
	v_add_f32_e32 v0, v150, v0
	v_add_f32_e32 v0, v151, v0
	v_cvt_pk_bf16_f32 v2, v144, v145
	v_cvt_pk_bf16_f32 v3, v146, v147
	v_cvt_pk_bf16_f32 v4, v148, v149
	v_cvt_pk_bf16_f32 v5, v150, v151
	s_nop 1
	ds_read_b64 v[242:243], v240 offset:40960
	ds_read_b64 v[244:245], v241 offset:40960
	s_waitcnt lgkmcnt(12)
	v_mfma_f32_32x32x16_bf16 v[64:79], v[128:131], v[2:5], v[64:79]
	ds_read_b64 v[144:145], v240 offset:45056
	ds_read_b64 v[146:147], v241 offset:45056
	v_exp_f32_e32 v152, v152
	v_exp_f32_e32 v153, v153
	s_waitcnt lgkmcnt(12)
	v_mfma_f32_32x32x16_bf16 v[112:127], v[136:139], v[2:5], v[112:127]
	v_exp_f32_e32 v154, v154
	v_exp_f32_e32 v155, v155
	v_add_f32_e32 v0, v152, v0
	v_add_f32_e32 v0, v153, v0
	s_waitcnt lgkmcnt(10)
	v_mfma_f32_32x32x16_bf16 v[48:63], v[140:143], v[2:5], v[48:63]
	v_exp_f32_e32 v156, v156
	v_exp_f32_e32 v157, v157
	v_add_f32_e32 v0, v154, v0
	v_add_f32_e32 v0, v155, v0
	s_waitcnt lgkmcnt(8)
	v_mfma_f32_32x32x16_bf16 v[32:47], v[132:135], v[2:5], v[32:47]
	v_exp_f32_e32 v158, v158
	v_exp_f32_e32 v159, v159
	v_add_f32_e32 v0, v156, v0
	v_add_f32_e32 v0, v157, v0
	v_add_f32_e32 v0, v158, v0
	v_add_f32_e32 v0, v159, v0
	v_cvt_pk_bf16_f32 v2, v152, v153
	v_cvt_pk_bf16_f32 v3, v154, v155
	v_cvt_pk_bf16_f32 v4, v156, v157
	v_cvt_pk_bf16_f32 v5, v158, v159
	s_nop 1
	s_waitcnt vmcnt(0) lgkmcnt(0)
	s_mov_b64 s[24:25], exec
	s_mov_b64 exec, 1
	v_mov_b32_e32 v248, s33
	v_mov_b32_e32 v249, 1
	ds_add_u32 v248, v249 offset:8
	s_mov_b64 exec, s[24:25]
	s_waitcnt lgkmcnt(6)
	v_mfma_f32_32x32x16_bf16 v[64:79], v[6:9], v[2:5], v[64:79]
	s_waitcnt lgkmcnt(4)
	v_mfma_f32_32x32x16_bf16 v[48:63], v[10:13], v[2:5], v[48:63]
	s_waitcnt lgkmcnt(2)
	v_mfma_f32_32x32x16_bf16 v[32:47], v[242:245], v[2:5], v[32:47]
	s_waitcnt lgkmcnt(0)
	v_mfma_f32_32x32x16_bf16 v[112:127], v[144:147], v[2:5], v[112:127]
	v_add_f32_e32 v224, v0, v224
	s_or_b64 exec, exec, s[20:21]
	s_branch .LBB0_1431
